# stick-breaking blocks: unmasked copy of each 32-key block body for blocks below the diagonal (no per-element index compare / select)
# speedup vs baseline: 1.0046x; 1.0046x over previous
.LBB0_342:
	s_mul_i32 s44, s65, 0xa000
	s_add_i32 s44, s44, 0
	v_add_u32_e32 v64, s44, v141
	v_add3_u32 v65, s44, v143, v144
	s_add_i32 s44, s62, 32
	s_cmp_ge_i32 s44, s60
	s_cselect_b64 s[44:45], -1, 0
	s_or_b64 s[44:45], s[44:45], s[42:43]
	s_and_b64 vcc, exec, s[44:45]
	v_add_u32_e32 v149, v64, v120
	v_add_u32_e32 v147, v65, v145
	v_add_u32_e32 v148, s62, v142
	s_cbranch_vccnz .LBB0_344
	ds_read_b128 v[64:67], v149 offset:8704
	ds_read_b128 v[112:115], v149 offset:8736
	ds_read_b128 v[116:119], v149 offset:8768
	s_add_i32 s42, s62, 63
	s_cmp_lt_i32 s42, s56
	s_cselect_b64 s[42:43], -1, 0
	s_cbranch_scc1 .Lsb_fast_a
	s_waitcnt lgkmcnt(0)
	v_mfma_f32_32x32x16_bf16 v[64:79], v[64:67], v[80:83], 0
	ds_read_b128 v[150:153], v149 offset:8800
	v_mfma_f32_32x32x16_bf16 v[64:79], v[112:115], v[84:87], v[64:79]
	ds_read_b128 v[112:115], v149 offset:8832
	v_mfma_f32_32x32x16_bf16 v[64:79], v[116:119], v[88:91], v[64:79]
	ds_read_b128 v[116:119], v149 offset:8864
	s_waitcnt lgkmcnt(0)
	v_mfma_f32_32x32x16_bf16 v[64:79], v[150:153], v[92:95], v[64:79]
	ds_read_b128 v[150:153], v149 offset:8896
	v_mfma_f32_32x32x16_bf16 v[64:79], v[112:115], v[96:99], v[64:79]
	ds_read_b128 v[112:115], v149 offset:8928
	v_mfma_f32_32x32x16_bf16 v[64:79], v[116:119], v[100:103], v[64:79]
	s_waitcnt lgkmcnt(0)
	v_mfma_f32_32x32x16_bf16 v[64:79], v[150:153], v[104:107], v[64:79]
	v_mfma_f32_32x32x16_bf16 v[64:79], v[112:115], v[108:111], v[64:79]
	ds_read_b64_tr_b16 v[116:117], v147 offset:27648
	ds_read_b64_tr_b16 v[118:119], v147 offset:30208
	ds_read_b64_tr_b16 v[114:115], v147 offset:30272
	ds_read_b64_tr_b16 v[112:113], v147 offset:27712
	s_nop 7
	v_max_f32_e32 v64, v64, v64
	v_min_f32_e32 v64, 0x42a00000, v64
	v_exp_f32_e32 v64, v64
	v_max_f32_e32 v65, v65, v65
	v_min_f32_e32 v65, 0x42a00000, v65
	v_exp_f32_e32 v65, v65
	v_add_f32_e32 v136, 1.0, v64
	v_rcp_f32_e32 v136, v136
	v_add_u32_e32 v137, 32, v148
	v_cmp_lt_i32_e32 vcc, v137, v122
	s_or_b64 vcc, s[42:43], vcc
	v_mul_f32_e32 v64, v64, v136
	v_cndmask_b32_e32 v150, 0, v64, vcc
	v_add_u32_e32 v64, 33, v148
	v_add_f32_e32 v137, 1.0, v65
	v_cndmask_b32_e32 v136, 1.0, v136, vcc
	v_cmp_lt_i32_e32 vcc, v64, v122
	v_max_f32_e32 v64, v66, v66
	v_rcp_f32_e32 v137, v137
	v_min_f32_e32 v64, 0x42a00000, v64
	v_exp_f32_e32 v66, v64
	s_or_b64 vcc, s[42:43], vcc
	v_mul_f32_e32 v65, v65, v137
	v_cndmask_b32_e32 v151, 0, v65, vcc
	v_add_f32_e32 v65, 1.0, v66
	v_max_f32_e32 v67, v67, v67
	v_rcp_f32_e32 v65, v65
	v_min_f32_e32 v67, 0x42a00000, v67
	v_exp_f32_e32 v67, v67
	v_cndmask_b32_e32 v64, 1.0, v137, vcc
	v_mul_f32_e32 v137, v66, v65
	v_add_u32_e32 v66, 34, v148
	v_cmp_lt_i32_e32 vcc, v66, v122
	v_add_f32_e32 v66, 1.0, v67
	v_rcp_f32_e32 v152, v66
	s_or_b64 vcc, s[42:43], vcc
	v_cndmask_b32_e32 v66, 1.0, v65, vcc
	v_cndmask_b32_e32 v153, 0, v137, vcc
	v_mul_f32_e32 v65, v67, v152
	v_add_u32_e32 v67, 35, v148
	v_cmp_lt_i32_e32 vcc, v67, v122
	v_max_f32_e32 v67, v68, v68
	v_min_f32_e32 v67, 0x42a00000, v67
	v_max_f32_e32 v69, v69, v69
	v_exp_f32_e32 v67, v67
	v_min_f32_e32 v69, 0x42a00000, v69
	v_exp_f32_e32 v69, v69
	s_or_b64 vcc, s[42:43], vcc
	v_cndmask_b32_e32 v68, 1.0, v152, vcc
	v_cndmask_b32_e32 v152, 0, v65, vcc
	v_add_f32_e32 v65, 1.0, v67
	v_add_u32_e32 v137, 40, v148
	v_rcp_f32_e32 v65, v65
	v_cmp_lt_i32_e32 vcc, v137, v122
	v_add_f32_e32 v137, 1.0, v69
	v_rcp_f32_e32 v137, v137
	v_mul_f32_e32 v67, v67, v65
	s_or_b64 vcc, s[42:43], vcc
	v_cndmask_b32_e32 v154, 0, v67, vcc
	v_mul_f32_e32 v67, v69, v137
	v_add_u32_e32 v69, 41, v148
	v_cndmask_b32_e32 v65, 1.0, v65, vcc
	v_cmp_lt_i32_e32 vcc, v69, v122
	v_max_f32_e32 v69, v70, v70
	v_min_f32_e32 v69, 0x42a00000, v69
	v_exp_f32_e32 v69, v69
	v_max_f32_e32 v70, v71, v71
	v_min_f32_e32 v70, 0x42a00000, v70
	s_or_b64 vcc, s[42:43], vcc
	v_exp_f32_e32 v70, v70
	v_cndmask_b32_e32 v156, 0, v67, vcc
	v_add_f32_e32 v67, 1.0, v69
	v_rcp_f32_e32 v67, v67
	v_add_u32_e32 v71, 42, v148
	v_cndmask_b32_e32 v155, 1.0, v137, vcc
	v_cmp_lt_i32_e32 vcc, v71, v122
	v_add_f32_e32 v71, 1.0, v70
	v_rcp_f32_e32 v71, v71
	v_mul_f32_e32 v69, v69, v67
	s_or_b64 vcc, s[42:43], vcc
	v_cndmask_b32_e32 v158, 0, v69, vcc
	v_add_u32_e32 v69, 43, v148
	v_cndmask_b32_e32 v157, 1.0, v67, vcc
	v_cmp_lt_i32_e32 vcc, v69, v122
	v_max_f32_e32 v69, v72, v72
	v_mul_f32_e32 v67, v70, v71
	v_min_f32_e32 v69, 0x42a00000, v69
	v_max_f32_e32 v70, v73, v73
	v_exp_f32_e32 v69, v69
	v_min_f32_e32 v70, 0x42a00000, v70
	v_exp_f32_e32 v70, v70
	s_or_b64 vcc, s[42:43], vcc
	v_cndmask_b32_e32 v159, 1.0, v71, vcc
	v_cndmask_b32_e32 v160, 0, v67, vcc
	v_add_f32_e32 v67, 1.0, v69
	v_add_u32_e32 v71, 48, v148
	v_rcp_f32_e32 v67, v67
	v_cmp_lt_i32_e32 vcc, v71, v122
	v_add_f32_e32 v71, 1.0, v70
	v_rcp_f32_e32 v71, v71
	v_mul_f32_e32 v69, v69, v67
	s_or_b64 vcc, s[42:43], vcc
	v_cndmask_b32_e32 v72, 0, v69, vcc
	v_mul_f32_e32 v69, v70, v71
	v_add_u32_e32 v70, 49, v148
	v_cndmask_b32_e32 v67, 1.0, v67, vcc
	v_cmp_lt_i32_e32 vcc, v70, v122
	v_max_f32_e32 v70, v74, v74
	v_max_f32_e32 v74, v75, v75
	v_min_f32_e32 v70, 0x42a00000, v70
	v_min_f32_e32 v74, 0x42a00000, v74
	v_exp_f32_e32 v70, v70
	v_exp_f32_e32 v74, v74
	s_or_b64 vcc, s[42:43], vcc
	v_add_u32_e32 v75, 50, v148
	v_cndmask_b32_e32 v71, 1.0, v71, vcc
	v_cndmask_b32_e32 v73, 0, v69, vcc
	v_add_f32_e32 v69, 1.0, v70
	v_cmp_lt_i32_e32 vcc, v75, v122
	v_add_f32_e32 v75, 1.0, v74
	v_rcp_f32_e32 v69, v69
	v_rcp_f32_e32 v75, v75
	s_or_b64 vcc, s[42:43], vcc
	v_max_f32_e32 v77, v77, v77
	v_mul_f32_e32 v70, v70, v69
	v_cndmask_b32_e32 v161, 1.0, v69, vcc
	v_mul_f32_e32 v69, v74, v75
	v_add_u32_e32 v74, 51, v148
	v_cndmask_b32_e32 v70, 0, v70, vcc
	v_cmp_lt_i32_e32 vcc, v74, v122
	v_max_f32_e32 v74, v76, v76
	v_min_f32_e32 v74, 0x42a00000, v74
	v_exp_f32_e32 v74, v74
	v_min_f32_e32 v77, 0x42a00000, v77
	s_or_b64 vcc, s[42:43], vcc
	v_exp_f32_e32 v77, v77
	v_cndmask_b32_e32 v76, 0, v69, vcc
	v_add_f32_e32 v69, 1.0, v74
	v_rcp_f32_e32 v69, v69
	v_add_u32_e32 v137, 56, v148
	v_max_f32_e32 v78, v78, v78
	v_cndmask_b32_e32 v75, 1.0, v75, vcc
	v_cmp_lt_i32_e32 vcc, v137, v122
	v_add_f32_e32 v137, 1.0, v77
	v_min_f32_e32 v78, 0x42a00000, v78
	v_rcp_f32_e32 v137, v137
	v_exp_f32_e32 v78, v78
	v_mul_f32_e32 v74, v74, v69
	s_or_b64 vcc, s[42:43], vcc
	v_add_u32_e32 v162, 57, v148
	v_cndmask_b32_e32 v69, 1.0, v69, vcc
	v_cndmask_b32_e32 v74, 0, v74, vcc
	v_cmp_lt_i32_e32 vcc, v162, v122
	s_or_b64 vcc, s[42:43], vcc
	v_mul_f32_e32 v77, v77, v137
	v_cndmask_b32_e32 v162, 1.0, v137, vcc
	v_add_f32_e32 v137, 1.0, v78
	v_rcp_f32_e32 v137, v137
	v_max_f32_e32 v79, v79, v79
	v_add_u32_e32 v163, 58, v148
	v_cndmask_b32_e32 v77, 0, v77, vcc
	v_min_f32_e32 v79, 0x42a00000, v79
	v_cmp_lt_i32_e32 vcc, v163, v122
	v_exp_f32_e32 v79, v79
	s_or_b64 vcc, s[42:43], vcc
	v_mul_f32_e32 v78, v78, v137
	v_cndmask_b32_e32 v164, 1.0, v137, vcc
	v_add_u32_e32 v137, 59, v148
	v_cndmask_b32_e32 v78, 0, v78, vcc
	v_cmp_lt_i32_e32 vcc, v137, v122
	v_mul_f32_e32 v65, v65, v155
	v_mul_f32_e32 v137, v157, v159
	v_mul_f32_e32 v137, v65, v137
	v_add_f32_e32 v163, 1.0, v79
	v_mov_b32_e32 v65, v137
	v_mov_b32_e32 v165, v137
	v_rcp_f32_e32 v163, v163
	s_nop 0
	v_permlane32_swap_b32_e32 v65, v165
	v_cndmask_b32_e64 v65, v65, v165, s[0:1]
	v_mul_f32_e32 v67, v67, v71
	v_mul_f32_e32 v165, v161, v75
	v_mul_f32_e32 v67, v67, v165
	s_or_b64 vcc, s[42:43], vcc
	v_mov_b32_e32 v165, v67
	v_mov_b32_e32 v166, v67
	v_mul_f32_e32 v79, v79, v163
	v_cndmask_b32_e32 v163, 1.0, v163, vcc
	v_permlane32_swap_b32_e32 v165, v166
	v_cndmask_b32_e64 v165, v165, v166, s[0:1]
	v_mul_f32_e32 v69, v69, v162
	v_mul_f32_e32 v166, v164, v163
	v_mul_f32_e32 v69, v69, v166
	v_mov_b32_e32 v166, v69
	v_mov_b32_e32 v167, v69
	s_nop 1
	v_permlane32_swap_b32_e32 v166, v167
	v_cndmask_b32_e64 v166, v166, v167, s[0:1]
	v_cndmask_b32_e64 v167, 1.0, v166, s[0:1]
	v_mul_f32_e32 v69, v69, v166
	v_mul_f32_e32 v167, v146, v167
	v_mul_f32_e32 v69, v146, v69
	v_cndmask_b32_e64 v146, 1.0, v165, s[0:1]
	v_mul_f32_e32 v146, v146, v69
	v_mul_f32_e32 v163, v163, v167
	v_mul_f32_e32 v75, v75, v146
	v_mul_f32_e32 v164, v164, v163
	v_mul_f32_e32 v161, v161, v75
	v_mul_f32_e32 v162, v162, v164
	v_mul_f32_e32 v71, v71, v161
	v_mul_f32_e32 v67, v67, v165
	v_mul_f32_e32 v74, v74, v162
	v_mul_f32_e32 v75, v70, v75
	v_mul_f32_e32 v161, v73, v161
	v_mul_f32_e32 v162, v72, v71
	v_pk_mul_f32 v[70:71], v[66:67], v[68:69]
	v_pk_mul_f32 v[72:73], v[136:137], v[64:65]
	v_mul_f32_e32 v76, v76, v146
	v_pk_mul_f32 v[72:73], v[72:73], v[70:71]
	v_cndmask_b32_e64 v146, 1.0, v65, s[0:1]
	v_mov_b32_e32 v65, v72
	v_mov_b32_e32 v67, v72
	s_nop 1
	v_permlane32_swap_b32_e32 v65, v67
	v_cndmask_b32_e64 v65, v65, v67, s[0:1]
	v_cndmask_b32_e64 v136, 1.0, v65, s[0:1]
	v_mul_f32_e32 v67, v146, v71
	v_mul_f32_e32 v136, v136, v73
	v_mul_f32_e32 v69, v159, v67
	v_mul_f32_e32 v68, v68, v136
	v_mul_f32_e32 v70, v157, v69
	v_mul_f32_e32 v66, v66, v68
	v_cndmask_b32_e32 v79, 0, v79, vcc
	v_mul_f32_e32 v71, v155, v70
	v_mul_f32_e32 v64, v64, v66
	v_mul_f32_e32 v65, v72, v65
	v_mul_f32_e32 v79, v79, v167
	v_mul_f32_e32 v78, v78, v163
	v_mul_f32_e32 v77, v77, v164
	v_mul_f32_e32 v67, v160, v67
	v_mul_f32_e32 v69, v158, v69
	v_mul_f32_e32 v70, v156, v70
	v_mul_f32_e32 v71, v154, v71
	v_mul_f32_e32 v136, v152, v136
	v_mul_f32_e32 v68, v153, v68
	v_mul_f32_e32 v66, v151, v66
	v_mul_f32_e32 v64, v150, v64
	v_mul_f32_e32 v146, v65, v73
	v_cvt_pk_bf16_f32 v64, v64, v66
	v_cvt_pk_bf16_f32 v65, v68, v136
	v_cvt_pk_bf16_f32 v66, v71, v70
	v_cvt_pk_bf16_f32 v67, v69, v67
	v_cvt_pk_bf16_f32 v68, v162, v161
	v_cvt_pk_bf16_f32 v69, v75, v76
	v_cvt_pk_bf16_f32 v70, v74, v77
	v_cvt_pk_bf16_f32 v71, v78, v79
	v_cmp_gt_f32_e32 vcc, s55, v146
	s_waitcnt lgkmcnt(0)
	v_mfma_f32_32x32x16_bf16 v[48:63], v[116:119], v[64:67], v[48:63]
	ds_read_b64_tr_b16 v[72:73], v147 offset:27776
	ds_read_b64_tr_b16 v[74:75], v147 offset:30336
	v_mfma_f32_32x32x16_bf16 v[32:47], v[112:115], v[64:67], v[32:47]
	ds_read_b64_tr_b16 v[76:77], v147 offset:27840
	ds_read_b64_tr_b16 v[78:79], v147 offset:30400
	s_waitcnt lgkmcnt(0)
	v_mfma_f32_32x32x16_bf16 v[16:31], v[72:75], v[64:67], v[16:31]
	ds_read_b64_tr_b16 v[112:113], v147 offset:32768
	ds_read_b64_tr_b16 v[114:115], v147 offset:35328
	v_mfma_f32_32x32x16_bf16 v[0:15], v[76:79], v[64:67], v[0:15]
	ds_read_b64_tr_b16 v[72:73], v147 offset:32832
	ds_read_b64_tr_b16 v[74:75], v147 offset:35392
	s_waitcnt lgkmcnt(0)
	v_mfma_f32_32x32x16_bf16 v[48:63], v[112:115], v[68:71], v[48:63]
	ds_read_b64_tr_b16 v[64:65], v147 offset:32896
	ds_read_b64_tr_b16 v[66:67], v147 offset:35456
	v_mfma_f32_32x32x16_bf16 v[32:47], v[72:75], v[68:71], v[32:47]
	ds_read_b64_tr_b16 v[76:77], v147 offset:32960
	ds_read_b64_tr_b16 v[78:79], v147 offset:35520
	s_waitcnt lgkmcnt(0)
	v_mfma_f32_32x32x16_bf16 v[16:31], v[64:67], v[68:71], v[16:31]
	v_mfma_f32_32x32x16_bf16 v[0:15], v[76:79], v[68:71], v[0:15]
	s_cmp_eq_u64 vcc, exec
	s_cselect_b64 s[42:43], -1, 0
.LBB0_344:
	s_cmp_ge_i32 s62, s60
	s_cselect_b64 s[44:45], -1, 0
	s_or_b64 s[44:45], s[44:45], s[42:43]
	s_and_b64 vcc, exec, s[44:45]
	s_cbranch_vccnz .LBB0_348
	ds_read_b128 v[64:67], v149
	ds_read_b128 v[112:115], v149 offset:32
	ds_read_b128 v[116:119], v149 offset:64
	s_add_i32 s42, s62, 31
	s_cmp_lt_i32 s42, s56
	s_cselect_b64 s[42:43], -1, 0
	s_cbranch_scc1 .Lsb_fast_b
	s_waitcnt lgkmcnt(0)
	v_mfma_f32_32x32x16_bf16 v[64:79], v[64:67], v[80:83], 0
	ds_read_b128 v[150:153], v149 offset:96
	v_mfma_f32_32x32x16_bf16 v[64:79], v[112:115], v[84:87], v[64:79]
	ds_read_b128 v[112:115], v149 offset:128
	v_mfma_f32_32x32x16_bf16 v[64:79], v[116:119], v[88:91], v[64:79]
	ds_read_b128 v[116:119], v149 offset:160
	s_waitcnt lgkmcnt(0)
	v_mfma_f32_32x32x16_bf16 v[64:79], v[150:153], v[92:95], v[64:79]
	ds_read_b128 v[150:153], v149 offset:192
	v_mfma_f32_32x32x16_bf16 v[64:79], v[112:115], v[96:99], v[64:79]
	ds_read_b128 v[112:115], v149 offset:224
	v_mfma_f32_32x32x16_bf16 v[64:79], v[116:119], v[100:103], v[64:79]
	s_waitcnt lgkmcnt(0)
	v_mfma_f32_32x32x16_bf16 v[64:79], v[150:153], v[104:107], v[64:79]
	v_mfma_f32_32x32x16_bf16 v[64:79], v[112:115], v[108:111], v[64:79]
	ds_read_b64_tr_b16 v[116:117], v147 offset:17408
	ds_read_b64_tr_b16 v[118:119], v147 offset:19968
	ds_read_b64_tr_b16 v[114:115], v147 offset:20032
	ds_read_b64_tr_b16 v[112:113], v147 offset:17472
	s_nop 7
	v_max_f32_e32 v64, v64, v64
	v_min_f32_e32 v64, 0x42a00000, v64
	v_exp_f32_e32 v64, v64
	v_max_f32_e32 v65, v65, v65
	v_min_f32_e32 v65, 0x42a00000, v65
	v_exp_f32_e32 v65, v65
	v_add_f32_e32 v136, 1.0, v64
	v_rcp_f32_e32 v136, v136
	v_cmp_lt_i32_e32 vcc, v148, v122
	s_or_b64 vcc, s[42:43], vcc
	v_add_f32_e32 v137, 1.0, v65
	v_mul_f32_e32 v64, v64, v136
	v_cndmask_b32_e32 v149, 0, v64, vcc
	v_add_u32_e32 v64, 1, v148
	v_cndmask_b32_e32 v136, 1.0, v136, vcc
	v_cmp_lt_i32_e32 vcc, v64, v122
	v_max_f32_e32 v64, v66, v66
	v_rcp_f32_e32 v137, v137
	v_min_f32_e32 v64, 0x42a00000, v64
	v_exp_f32_e32 v66, v64
	s_or_b64 vcc, s[42:43], vcc
	v_mul_f32_e32 v65, v65, v137
	v_cndmask_b32_e32 v150, 0, v65, vcc
	v_add_f32_e32 v65, 1.0, v66
	v_max_f32_e32 v67, v67, v67
	v_rcp_f32_e32 v65, v65
	v_min_f32_e32 v67, 0x42a00000, v67
	v_exp_f32_e32 v67, v67
	v_cndmask_b32_e32 v64, 1.0, v137, vcc
	v_mul_f32_e32 v137, v66, v65
	v_add_u32_e32 v66, 2, v148
	v_cmp_lt_i32_e32 vcc, v66, v122
	v_add_f32_e32 v66, 1.0, v67
	v_rcp_f32_e32 v151, v66
	s_or_b64 vcc, s[42:43], vcc
	v_cndmask_b32_e32 v66, 1.0, v65, vcc
	v_cndmask_b32_e32 v152, 0, v137, vcc
	v_mul_f32_e32 v65, v67, v151
	v_add_u32_e32 v67, 3, v148
	v_cmp_lt_i32_e32 vcc, v67, v122
	v_max_f32_e32 v67, v68, v68
	v_min_f32_e32 v67, 0x42a00000, v67
	v_max_f32_e32 v69, v69, v69
	v_exp_f32_e32 v67, v67
	v_min_f32_e32 v69, 0x42a00000, v69
	v_exp_f32_e32 v69, v69
	s_or_b64 vcc, s[42:43], vcc
	v_cndmask_b32_e32 v68, 1.0, v151, vcc
	v_cndmask_b32_e32 v151, 0, v65, vcc
	v_add_f32_e32 v65, 1.0, v67
	v_add_u32_e32 v137, 8, v148
	v_rcp_f32_e32 v65, v65
	v_cmp_lt_i32_e32 vcc, v137, v122
	v_add_f32_e32 v137, 1.0, v69
	v_rcp_f32_e32 v137, v137
	v_mul_f32_e32 v67, v67, v65
	s_or_b64 vcc, s[42:43], vcc
	v_cndmask_b32_e32 v153, 0, v67, vcc
	v_mul_f32_e32 v67, v69, v137
	v_add_u32_e32 v69, 9, v148
	v_cndmask_b32_e32 v65, 1.0, v65, vcc
	v_cmp_lt_i32_e32 vcc, v69, v122
	v_max_f32_e32 v69, v70, v70
	v_min_f32_e32 v69, 0x42a00000, v69
	v_exp_f32_e32 v69, v69
	v_max_f32_e32 v70, v71, v71
	v_min_f32_e32 v70, 0x42a00000, v70
	s_or_b64 vcc, s[42:43], vcc
	v_exp_f32_e32 v70, v70
	v_cndmask_b32_e32 v155, 0, v67, vcc
	v_add_f32_e32 v67, 1.0, v69
	v_rcp_f32_e32 v67, v67
	v_add_u32_e32 v71, 10, v148
	v_cndmask_b32_e32 v154, 1.0, v137, vcc
	v_cmp_lt_i32_e32 vcc, v71, v122
	v_add_f32_e32 v71, 1.0, v70
	v_rcp_f32_e32 v71, v71
	v_mul_f32_e32 v69, v69, v67
	s_or_b64 vcc, s[42:43], vcc
	v_cndmask_b32_e32 v157, 0, v69, vcc
	v_add_u32_e32 v69, 11, v148
	v_cndmask_b32_e32 v156, 1.0, v67, vcc
	v_cmp_lt_i32_e32 vcc, v69, v122
	v_max_f32_e32 v69, v72, v72
	v_mul_f32_e32 v67, v70, v71
	v_min_f32_e32 v69, 0x42a00000, v69
	v_max_f32_e32 v70, v73, v73
	v_exp_f32_e32 v69, v69
	v_min_f32_e32 v70, 0x42a00000, v70
	v_exp_f32_e32 v70, v70
	s_or_b64 vcc, s[42:43], vcc
	v_cndmask_b32_e32 v158, 1.0, v71, vcc
	v_cndmask_b32_e32 v159, 0, v67, vcc
	v_add_f32_e32 v67, 1.0, v69
	v_add_u32_e32 v71, 16, v148
	v_rcp_f32_e32 v67, v67
	v_cmp_lt_i32_e32 vcc, v71, v122
	v_add_f32_e32 v71, 1.0, v70
	v_rcp_f32_e32 v71, v71
	v_mul_f32_e32 v69, v69, v67
	s_or_b64 vcc, s[42:43], vcc
	v_cndmask_b32_e32 v72, 0, v69, vcc
	v_mul_f32_e32 v69, v70, v71
	v_add_u32_e32 v70, 17, v148
	v_cndmask_b32_e32 v67, 1.0, v67, vcc
	v_cmp_lt_i32_e32 vcc, v70, v122
	v_max_f32_e32 v70, v74, v74
	v_max_f32_e32 v74, v75, v75
	v_min_f32_e32 v70, 0x42a00000, v70
	v_min_f32_e32 v74, 0x42a00000, v74
	v_exp_f32_e32 v70, v70
	v_exp_f32_e32 v74, v74
	s_or_b64 vcc, s[42:43], vcc
	v_add_u32_e32 v75, 18, v148
	v_cndmask_b32_e32 v71, 1.0, v71, vcc
	v_cndmask_b32_e32 v73, 0, v69, vcc
	v_add_f32_e32 v69, 1.0, v70
	v_cmp_lt_i32_e32 vcc, v75, v122
	v_add_f32_e32 v75, 1.0, v74
	v_rcp_f32_e32 v69, v69
	v_rcp_f32_e32 v75, v75
	s_or_b64 vcc, s[42:43], vcc
	v_max_f32_e32 v77, v77, v77
	v_mul_f32_e32 v70, v70, v69
	v_cndmask_b32_e32 v160, 1.0, v69, vcc
	v_mul_f32_e32 v69, v74, v75
	v_add_u32_e32 v74, 19, v148
	v_cndmask_b32_e32 v70, 0, v70, vcc
	v_cmp_lt_i32_e32 vcc, v74, v122
	v_max_f32_e32 v74, v76, v76
	v_min_f32_e32 v74, 0x42a00000, v74
	v_exp_f32_e32 v74, v74
	v_min_f32_e32 v77, 0x42a00000, v77
	s_or_b64 vcc, s[42:43], vcc
	v_exp_f32_e32 v77, v77
	v_cndmask_b32_e32 v76, 0, v69, vcc
	v_add_f32_e32 v69, 1.0, v74
	v_rcp_f32_e32 v69, v69
	v_add_u32_e32 v137, 24, v148
	v_max_f32_e32 v78, v78, v78
	v_cndmask_b32_e32 v75, 1.0, v75, vcc
	v_cmp_lt_i32_e32 vcc, v137, v122
	v_add_f32_e32 v137, 1.0, v77
	v_min_f32_e32 v78, 0x42a00000, v78
	v_rcp_f32_e32 v137, v137
	v_exp_f32_e32 v78, v78
	v_mul_f32_e32 v74, v74, v69
	s_or_b64 vcc, s[42:43], vcc
	v_add_u32_e32 v161, 25, v148
	v_max_f32_e32 v79, v79, v79
	v_cndmask_b32_e32 v69, 1.0, v69, vcc
	v_cndmask_b32_e32 v74, 0, v74, vcc
	v_cmp_lt_i32_e32 vcc, v161, v122
	v_min_f32_e32 v79, 0x42a00000, v79
	s_or_b64 vcc, s[42:43], vcc
	v_exp_f32_e32 v79, v79
	v_mul_f32_e32 v77, v77, v137
	v_cndmask_b32_e32 v161, 1.0, v137, vcc
	v_add_f32_e32 v137, 1.0, v78
	v_rcp_f32_e32 v137, v137
	v_add_u32_e32 v162, 26, v148
	v_cndmask_b32_e32 v77, 0, v77, vcc
	v_cmp_lt_i32_e32 vcc, v162, v122
	v_add_f32_e32 v162, 1.0, v79
	v_rcp_f32_e32 v162, v162
	s_or_b64 vcc, s[42:43], vcc
	v_mul_f32_e32 v78, v78, v137
	v_cndmask_b32_e32 v163, 1.0, v137, vcc
	v_add_u32_e32 v137, 27, v148
	v_cndmask_b32_e32 v78, 0, v78, vcc
	v_cmp_lt_i32_e32 vcc, v137, v122
	v_mul_f32_e32 v65, v65, v154
	v_mul_f32_e32 v137, v156, v158
	s_or_b64 vcc, s[42:43], vcc
	v_mul_f32_e32 v137, v65, v137
	v_mul_f32_e32 v79, v79, v162
	v_cndmask_b32_e32 v148, 1.0, v162, vcc
	v_mov_b32_e32 v65, v137
	v_mov_b32_e32 v162, v137
	s_nop 1
	v_permlane32_swap_b32_e32 v65, v162
	v_cndmask_b32_e64 v65, v65, v162, s[0:1]
	v_mul_f32_e32 v67, v67, v71
	v_mul_f32_e32 v162, v160, v75
	v_mul_f32_e32 v67, v67, v162
	v_mov_b32_e32 v162, v67
	v_mov_b32_e32 v164, v67
	s_nop 1
	v_permlane32_swap_b32_e32 v162, v164
	v_cndmask_b32_e64 v162, v162, v164, s[0:1]
	v_mul_f32_e32 v69, v69, v161
	v_mul_f32_e32 v164, v163, v148
	v_mul_f32_e32 v69, v69, v164
	v_mov_b32_e32 v164, v69
	v_mov_b32_e32 v165, v69
	s_nop 1
	v_permlane32_swap_b32_e32 v164, v165
	v_cndmask_b32_e64 v164, v164, v165, s[0:1]
	v_cndmask_b32_e64 v165, 1.0, v164, s[0:1]
	v_mul_f32_e32 v69, v69, v164
	v_mul_f32_e32 v165, v146, v165
	v_mul_f32_e32 v69, v146, v69
	v_cndmask_b32_e64 v146, 1.0, v162, s[0:1]
	v_mul_f32_e32 v146, v146, v69
	v_mul_f32_e32 v148, v148, v165
	v_mul_f32_e32 v75, v75, v146
	v_mul_f32_e32 v163, v163, v148
	v_mul_f32_e32 v78, v78, v148
	v_mul_f32_e32 v148, v160, v75
	v_mul_f32_e32 v71, v71, v148
	v_mul_f32_e32 v67, v67, v162
	v_mul_f32_e32 v75, v70, v75
	v_mul_f32_e32 v148, v73, v148
	v_mul_f32_e32 v160, v72, v71
	v_pk_mul_f32 v[70:71], v[66:67], v[68:69]
	v_pk_mul_f32 v[72:73], v[136:137], v[64:65]
	v_mul_f32_e32 v76, v76, v146
	v_pk_mul_f32 v[72:73], v[72:73], v[70:71]
	v_cndmask_b32_e64 v146, 1.0, v65, s[0:1]
	v_mov_b32_e32 v65, v72
	v_mov_b32_e32 v67, v72
	s_nop 1
	v_permlane32_swap_b32_e32 v65, v67
	v_cndmask_b32_e64 v65, v65, v67, s[0:1]
	v_cndmask_b32_e64 v136, 1.0, v65, s[0:1]
	v_mul_f32_e32 v67, v146, v71
	v_mul_f32_e32 v136, v136, v73
	v_mul_f32_e32 v69, v158, v67
	v_mul_f32_e32 v68, v68, v136
	v_mul_f32_e32 v70, v156, v69
	v_mul_f32_e32 v66, v66, v68
	v_cndmask_b32_e32 v79, 0, v79, vcc
	v_mul_f32_e32 v161, v161, v163
	v_mul_f32_e32 v71, v154, v70
	v_mul_f32_e32 v64, v64, v66
	v_mul_f32_e32 v65, v72, v65
	v_mul_f32_e32 v79, v79, v165
	v_mul_f32_e32 v77, v77, v163
	v_mul_f32_e32 v74, v74, v161
	v_mul_f32_e32 v67, v159, v67
	v_mul_f32_e32 v69, v157, v69
	v_mul_f32_e32 v70, v155, v70
	v_mul_f32_e32 v71, v153, v71
	v_mul_f32_e32 v136, v151, v136
	v_mul_f32_e32 v68, v152, v68
	v_mul_f32_e32 v66, v150, v66
	v_mul_f32_e32 v64, v149, v64
	v_mul_f32_e32 v146, v65, v73
	v_cvt_pk_bf16_f32 v64, v64, v66
	v_cvt_pk_bf16_f32 v65, v68, v136
	v_cvt_pk_bf16_f32 v66, v71, v70
	v_cvt_pk_bf16_f32 v67, v69, v67
	v_cvt_pk_bf16_f32 v68, v160, v148
	v_cvt_pk_bf16_f32 v69, v75, v76
	v_cvt_pk_bf16_f32 v70, v74, v77
	v_cvt_pk_bf16_f32 v71, v78, v79
	v_cmp_gt_f32_e32 vcc, s55, v146
	s_waitcnt lgkmcnt(0)
	v_mfma_f32_32x32x16_bf16 v[48:63], v[116:119], v[64:67], v[48:63]
	ds_read_b64_tr_b16 v[72:73], v147 offset:17536
	ds_read_b64_tr_b16 v[74:75], v147 offset:20096
	v_mfma_f32_32x32x16_bf16 v[32:47], v[112:115], v[64:67], v[32:47]
	ds_read_b64_tr_b16 v[76:77], v147 offset:17600
	ds_read_b64_tr_b16 v[78:79], v147 offset:20160
	s_waitcnt lgkmcnt(0)
	v_mfma_f32_32x32x16_bf16 v[16:31], v[72:75], v[64:67], v[16:31]
	ds_read_b64_tr_b16 v[112:113], v147 offset:22528
	ds_read_b64_tr_b16 v[114:115], v147 offset:25088
	v_mfma_f32_32x32x16_bf16 v[0:15], v[76:79], v[64:67], v[0:15]
	ds_read_b64_tr_b16 v[72:73], v147 offset:22592
	ds_read_b64_tr_b16 v[74:75], v147 offset:25152
	s_waitcnt lgkmcnt(0)
	v_mfma_f32_32x32x16_bf16 v[48:63], v[112:115], v[68:71], v[48:63]
	ds_read_b64_tr_b16 v[64:65], v147 offset:22656
	ds_read_b64_tr_b16 v[66:67], v147 offset:25216
	v_mfma_f32_32x32x16_bf16 v[32:47], v[72:75], v[68:71], v[32:47]
	ds_read_b64_tr_b16 v[76:77], v147 offset:22720
	ds_read_b64_tr_b16 v[78:79], v147 offset:25280
	s_waitcnt lgkmcnt(0)
	v_mfma_f32_32x32x16_bf16 v[16:31], v[64:67], v[68:71], v[16:31]
	v_mfma_f32_32x32x16_bf16 v[0:15], v[76:79], v[68:71], v[0:15]
	s_cmp_eq_u64 vcc, exec
	s_cselect_b64 s[42:43], -1, 0
.Lsb_join_b:
	s_and_saveexec_b64 s[44:45], s[4:5]
	s_cbranch_execnz .LBB0_349

.Lsb_fast_a:
	s_waitcnt lgkmcnt(0)
	v_mfma_f32_32x32x16_bf16 v[64:79], v[64:67], v[80:83], 0
	ds_read_b128 v[150:153], v149 offset:8800
	v_mfma_f32_32x32x16_bf16 v[64:79], v[112:115], v[84:87], v[64:79]
	ds_read_b128 v[112:115], v149 offset:8832
	v_mfma_f32_32x32x16_bf16 v[64:79], v[116:119], v[88:91], v[64:79]
	ds_read_b128 v[116:119], v149 offset:8864
	s_waitcnt lgkmcnt(0)
	v_mfma_f32_32x32x16_bf16 v[64:79], v[150:153], v[92:95], v[64:79]
	ds_read_b128 v[150:153], v149 offset:8896
	v_mfma_f32_32x32x16_bf16 v[64:79], v[112:115], v[96:99], v[64:79]
	ds_read_b128 v[112:115], v149 offset:8928
	v_mfma_f32_32x32x16_bf16 v[64:79], v[116:119], v[100:103], v[64:79]
	s_waitcnt lgkmcnt(0)
	v_mfma_f32_32x32x16_bf16 v[64:79], v[150:153], v[104:107], v[64:79]
	v_mfma_f32_32x32x16_bf16 v[64:79], v[112:115], v[108:111], v[64:79]
	ds_read_b64_tr_b16 v[116:117], v147 offset:27648
	ds_read_b64_tr_b16 v[118:119], v147 offset:30208
	ds_read_b64_tr_b16 v[114:115], v147 offset:30272
	ds_read_b64_tr_b16 v[112:113], v147 offset:27712
	s_nop 7
	v_max_f32_e32 v64, v64, v64
	v_min_f32_e32 v64, 0x42a00000, v64
	v_exp_f32_e32 v64, v64
	v_max_f32_e32 v65, v65, v65
	v_min_f32_e32 v65, 0x42a00000, v65
	v_exp_f32_e32 v65, v65
	v_add_f32_e32 v136, 1.0, v64
	v_rcp_f32_e32 v136, v136
	s_nop 0
	v_mul_f32_e32 v64, v64, v136
	v_mov_b32_e32 v150, v64
	v_add_f32_e32 v137, 1.0, v65
	v_max_f32_e32 v64, v66, v66
	v_rcp_f32_e32 v137, v137
	v_min_f32_e32 v64, 0x42a00000, v64
	v_exp_f32_e32 v66, v64
	v_mul_f32_e32 v65, v65, v137
	v_mov_b32_e32 v151, v65
	v_add_f32_e32 v65, 1.0, v66
	v_max_f32_e32 v67, v67, v67
	v_rcp_f32_e32 v65, v65
	v_min_f32_e32 v67, 0x42a00000, v67
	v_exp_f32_e32 v67, v67
	v_mov_b32_e32 v64, v137
	v_mul_f32_e32 v137, v66, v65
	v_add_f32_e32 v66, 1.0, v67
	v_rcp_f32_e32 v152, v66
	v_mov_b32_e32 v66, v65
	v_mov_b32_e32 v153, v137
	v_mul_f32_e32 v65, v67, v152
	v_max_f32_e32 v67, v68, v68
	v_min_f32_e32 v67, 0x42a00000, v67
	v_max_f32_e32 v69, v69, v69
	v_exp_f32_e32 v67, v67
	v_min_f32_e32 v69, 0x42a00000, v69
	v_exp_f32_e32 v69, v69
	v_mov_b32_e32 v68, v152
	v_mov_b32_e32 v152, v65
	v_add_f32_e32 v65, 1.0, v67
	v_rcp_f32_e32 v65, v65
	v_add_f32_e32 v137, 1.0, v69
	v_rcp_f32_e32 v137, v137
	v_mul_f32_e32 v67, v67, v65
	v_mov_b32_e32 v154, v67
	v_mul_f32_e32 v67, v69, v137
	v_max_f32_e32 v69, v70, v70
	v_min_f32_e32 v69, 0x42a00000, v69
	v_exp_f32_e32 v69, v69
	v_max_f32_e32 v70, v71, v71
	v_min_f32_e32 v70, 0x42a00000, v70
	v_exp_f32_e32 v70, v70
	v_mov_b32_e32 v156, v67
	v_add_f32_e32 v67, 1.0, v69
	v_rcp_f32_e32 v67, v67
	v_mov_b32_e32 v155, v137
	v_add_f32_e32 v71, 1.0, v70
	v_rcp_f32_e32 v71, v71
	v_mul_f32_e32 v69, v69, v67
	v_mov_b32_e32 v158, v69
	v_mov_b32_e32 v157, v67
	v_max_f32_e32 v69, v72, v72
	v_mul_f32_e32 v67, v70, v71
	v_min_f32_e32 v69, 0x42a00000, v69
	v_max_f32_e32 v70, v73, v73
	v_exp_f32_e32 v69, v69
	v_min_f32_e32 v70, 0x42a00000, v70
	v_exp_f32_e32 v70, v70
	v_mov_b32_e32 v159, v71
	v_mov_b32_e32 v160, v67
	v_add_f32_e32 v67, 1.0, v69
	v_rcp_f32_e32 v67, v67
	v_add_f32_e32 v71, 1.0, v70
	v_rcp_f32_e32 v71, v71
	v_mul_f32_e32 v69, v69, v67
	v_mov_b32_e32 v72, v69
	v_mul_f32_e32 v69, v70, v71
	v_max_f32_e32 v70, v74, v74
	v_max_f32_e32 v74, v75, v75
	v_min_f32_e32 v70, 0x42a00000, v70
	v_min_f32_e32 v74, 0x42a00000, v74
	v_exp_f32_e32 v70, v70
	v_exp_f32_e32 v74, v74
	v_mov_b32_e32 v73, v69
	v_add_f32_e32 v69, 1.0, v70
	v_add_f32_e32 v75, 1.0, v74
	v_rcp_f32_e32 v69, v69
	v_rcp_f32_e32 v75, v75
	v_max_f32_e32 v77, v77, v77
	v_mul_f32_e32 v70, v70, v69
	v_mov_b32_e32 v161, v69
	v_mul_f32_e32 v69, v74, v75
	v_max_f32_e32 v74, v76, v76
	v_min_f32_e32 v74, 0x42a00000, v74
	v_exp_f32_e32 v74, v74
	v_min_f32_e32 v77, 0x42a00000, v77
	v_exp_f32_e32 v77, v77
	v_mov_b32_e32 v76, v69
	v_add_f32_e32 v69, 1.0, v74
	v_rcp_f32_e32 v69, v69
	v_max_f32_e32 v78, v78, v78
	v_add_f32_e32 v137, 1.0, v77
	v_min_f32_e32 v78, 0x42a00000, v78
	v_rcp_f32_e32 v137, v137
	v_exp_f32_e32 v78, v78
	v_mul_f32_e32 v74, v74, v69
	v_mul_f32_e32 v77, v77, v137
	v_mov_b32_e32 v162, v137
	v_add_f32_e32 v137, 1.0, v78
	v_rcp_f32_e32 v137, v137
	v_max_f32_e32 v79, v79, v79
	v_min_f32_e32 v79, 0x42a00000, v79
	v_exp_f32_e32 v79, v79
	v_mul_f32_e32 v78, v78, v137
	v_mov_b32_e32 v164, v137
	v_mul_f32_e32 v65, v65, v155
	v_mul_f32_e32 v137, v157, v159
	v_mul_f32_e32 v137, v65, v137
	v_add_f32_e32 v163, 1.0, v79
	v_mov_b32_e32 v65, v137
	v_mov_b32_e32 v165, v137
	v_rcp_f32_e32 v163, v163
	s_nop 0
	v_permlane32_swap_b32_e32 v65, v165
	v_cndmask_b32_e64 v65, v65, v165, s[0:1]
	v_mul_f32_e32 v67, v67, v71
	v_mul_f32_e32 v165, v161, v75
	v_mul_f32_e32 v67, v67, v165
	v_mov_b32_e32 v165, v67
	v_mov_b32_e32 v166, v67
	v_mul_f32_e32 v79, v79, v163
	s_nop 0
	v_permlane32_swap_b32_e32 v165, v166
	v_cndmask_b32_e64 v165, v165, v166, s[0:1]
	v_mul_f32_e32 v69, v69, v162
	v_mul_f32_e32 v166, v164, v163
	v_mul_f32_e32 v69, v69, v166
	v_mov_b32_e32 v166, v69
	v_mov_b32_e32 v167, v69
	s_nop 1
	v_permlane32_swap_b32_e32 v166, v167
	v_cndmask_b32_e64 v166, v166, v167, s[0:1]
	v_cndmask_b32_e64 v167, 1.0, v166, s[0:1]
	v_mul_f32_e32 v69, v69, v166
	v_mul_f32_e32 v167, v146, v167
	v_mul_f32_e32 v69, v146, v69
	v_cndmask_b32_e64 v146, 1.0, v165, s[0:1]
	v_mul_f32_e32 v146, v146, v69
	v_mul_f32_e32 v163, v163, v167
	v_mul_f32_e32 v75, v75, v146
	v_mul_f32_e32 v164, v164, v163
	v_mul_f32_e32 v161, v161, v75
	v_mul_f32_e32 v162, v162, v164
	v_mul_f32_e32 v71, v71, v161
	v_mul_f32_e32 v67, v67, v165
	v_mul_f32_e32 v74, v74, v162
	v_mul_f32_e32 v75, v70, v75
	v_mul_f32_e32 v161, v73, v161
	v_mul_f32_e32 v162, v72, v71
	v_pk_mul_f32 v[70:71], v[66:67], v[68:69]
	v_pk_mul_f32 v[72:73], v[136:137], v[64:65]
	v_mul_f32_e32 v76, v76, v146
	v_pk_mul_f32 v[72:73], v[72:73], v[70:71]
	v_cndmask_b32_e64 v146, 1.0, v65, s[0:1]
	v_mov_b32_e32 v65, v72
	v_mov_b32_e32 v67, v72
	s_nop 1
	v_permlane32_swap_b32_e32 v65, v67
	v_cndmask_b32_e64 v65, v65, v67, s[0:1]
	v_cndmask_b32_e64 v136, 1.0, v65, s[0:1]
	v_mul_f32_e32 v67, v146, v71
	v_mul_f32_e32 v136, v136, v73
	v_mul_f32_e32 v69, v159, v67
	v_mul_f32_e32 v68, v68, v136
	v_mul_f32_e32 v70, v157, v69
	v_mul_f32_e32 v66, v66, v68
	v_mul_f32_e32 v71, v155, v70
	v_mul_f32_e32 v64, v64, v66
	v_mul_f32_e32 v65, v72, v65
	v_mul_f32_e32 v79, v79, v167
	v_mul_f32_e32 v78, v78, v163
	v_mul_f32_e32 v77, v77, v164
	v_mul_f32_e32 v67, v160, v67
	v_mul_f32_e32 v69, v158, v69
	v_mul_f32_e32 v70, v156, v70
	v_mul_f32_e32 v71, v154, v71
	v_mul_f32_e32 v136, v152, v136
	v_mul_f32_e32 v68, v153, v68
	v_mul_f32_e32 v66, v151, v66
	v_mul_f32_e32 v64, v150, v64
	v_mul_f32_e32 v146, v65, v73
	v_cvt_pk_bf16_f32 v64, v64, v66
	v_cvt_pk_bf16_f32 v65, v68, v136
	v_cvt_pk_bf16_f32 v66, v71, v70
	v_cvt_pk_bf16_f32 v67, v69, v67
	v_cvt_pk_bf16_f32 v68, v162, v161
	v_cvt_pk_bf16_f32 v69, v75, v76
	v_cvt_pk_bf16_f32 v70, v74, v77
	v_cvt_pk_bf16_f32 v71, v78, v79
	v_cmp_gt_f32_e32 vcc, s55, v146
	s_waitcnt lgkmcnt(0)
	v_mfma_f32_32x32x16_bf16 v[48:63], v[116:119], v[64:67], v[48:63]
	ds_read_b64_tr_b16 v[72:73], v147 offset:27776
	ds_read_b64_tr_b16 v[74:75], v147 offset:30336
	v_mfma_f32_32x32x16_bf16 v[32:47], v[112:115], v[64:67], v[32:47]
	ds_read_b64_tr_b16 v[76:77], v147 offset:27840
	ds_read_b64_tr_b16 v[78:79], v147 offset:30400
	s_waitcnt lgkmcnt(0)
	v_mfma_f32_32x32x16_bf16 v[16:31], v[72:75], v[64:67], v[16:31]
	ds_read_b64_tr_b16 v[112:113], v147 offset:32768
	ds_read_b64_tr_b16 v[114:115], v147 offset:35328
	v_mfma_f32_32x32x16_bf16 v[0:15], v[76:79], v[64:67], v[0:15]
	ds_read_b64_tr_b16 v[72:73], v147 offset:32832
	ds_read_b64_tr_b16 v[74:75], v147 offset:35392
	s_waitcnt lgkmcnt(0)
	v_mfma_f32_32x32x16_bf16 v[48:63], v[112:115], v[68:71], v[48:63]
	ds_read_b64_tr_b16 v[64:65], v147 offset:32896
	ds_read_b64_tr_b16 v[66:67], v147 offset:35456
	v_mfma_f32_32x32x16_bf16 v[32:47], v[72:75], v[68:71], v[32:47]
	ds_read_b64_tr_b16 v[76:77], v147 offset:32960
	ds_read_b64_tr_b16 v[78:79], v147 offset:35520
	s_waitcnt lgkmcnt(0)
	v_mfma_f32_32x32x16_bf16 v[16:31], v[64:67], v[68:71], v[16:31]
	v_mfma_f32_32x32x16_bf16 v[0:15], v[76:79], v[68:71], v[0:15]
	s_cmp_eq_u64 vcc, exec
	s_cselect_b64 s[42:43], -1, 0
	s_branch .LBB0_344
.Lsb_fast_b:
	s_waitcnt lgkmcnt(0)
	v_mfma_f32_32x32x16_bf16 v[64:79], v[64:67], v[80:83], 0
	ds_read_b128 v[150:153], v149 offset:96
	v_mfma_f32_32x32x16_bf16 v[64:79], v[112:115], v[84:87], v[64:79]
	ds_read_b128 v[112:115], v149 offset:128
	v_mfma_f32_32x32x16_bf16 v[64:79], v[116:119], v[88:91], v[64:79]
	ds_read_b128 v[116:119], v149 offset:160
	s_waitcnt lgkmcnt(0)
	v_mfma_f32_32x32x16_bf16 v[64:79], v[150:153], v[92:95], v[64:79]
	ds_read_b128 v[150:153], v149 offset:192
	v_mfma_f32_32x32x16_bf16 v[64:79], v[112:115], v[96:99], v[64:79]
	ds_read_b128 v[112:115], v149 offset:224
	v_mfma_f32_32x32x16_bf16 v[64:79], v[116:119], v[100:103], v[64:79]
	s_waitcnt lgkmcnt(0)
	v_mfma_f32_32x32x16_bf16 v[64:79], v[150:153], v[104:107], v[64:79]
	v_mfma_f32_32x32x16_bf16 v[64:79], v[112:115], v[108:111], v[64:79]
	ds_read_b64_tr_b16 v[116:117], v147 offset:17408
	ds_read_b64_tr_b16 v[118:119], v147 offset:19968
	ds_read_b64_tr_b16 v[114:115], v147 offset:20032
	ds_read_b64_tr_b16 v[112:113], v147 offset:17472
	s_nop 7
	v_max_f32_e32 v64, v64, v64
	v_min_f32_e32 v64, 0x42a00000, v64
	v_exp_f32_e32 v64, v64
	v_max_f32_e32 v65, v65, v65
	v_min_f32_e32 v65, 0x42a00000, v65
	v_exp_f32_e32 v65, v65
	v_add_f32_e32 v136, 1.0, v64
	v_rcp_f32_e32 v136, v136
	v_add_f32_e32 v137, 1.0, v65
	v_mul_f32_e32 v64, v64, v136
	v_mov_b32_e32 v149, v64
	v_max_f32_e32 v64, v66, v66
	v_rcp_f32_e32 v137, v137
	v_min_f32_e32 v64, 0x42a00000, v64
	v_exp_f32_e32 v66, v64
	v_mul_f32_e32 v65, v65, v137
	v_mov_b32_e32 v150, v65
	v_add_f32_e32 v65, 1.0, v66
	v_max_f32_e32 v67, v67, v67
	v_rcp_f32_e32 v65, v65
	v_min_f32_e32 v67, 0x42a00000, v67
	v_exp_f32_e32 v67, v67
	v_mov_b32_e32 v64, v137
	v_mul_f32_e32 v137, v66, v65
	v_add_f32_e32 v66, 1.0, v67
	v_rcp_f32_e32 v151, v66
	v_mov_b32_e32 v66, v65
	v_mov_b32_e32 v152, v137
	v_mul_f32_e32 v65, v67, v151
	v_max_f32_e32 v67, v68, v68
	v_min_f32_e32 v67, 0x42a00000, v67
	v_max_f32_e32 v69, v69, v69
	v_exp_f32_e32 v67, v67
	v_min_f32_e32 v69, 0x42a00000, v69
	v_exp_f32_e32 v69, v69
	v_mov_b32_e32 v68, v151
	v_mov_b32_e32 v151, v65
	v_add_f32_e32 v65, 1.0, v67
	v_rcp_f32_e32 v65, v65
	v_add_f32_e32 v137, 1.0, v69
	v_rcp_f32_e32 v137, v137
	v_mul_f32_e32 v67, v67, v65
	v_mov_b32_e32 v153, v67
	v_mul_f32_e32 v67, v69, v137
	v_max_f32_e32 v69, v70, v70
	v_min_f32_e32 v69, 0x42a00000, v69
	v_exp_f32_e32 v69, v69
	v_max_f32_e32 v70, v71, v71
	v_min_f32_e32 v70, 0x42a00000, v70
	v_exp_f32_e32 v70, v70
	v_mov_b32_e32 v155, v67
	v_add_f32_e32 v67, 1.0, v69
	v_rcp_f32_e32 v67, v67
	v_mov_b32_e32 v154, v137
	v_add_f32_e32 v71, 1.0, v70
	v_rcp_f32_e32 v71, v71
	v_mul_f32_e32 v69, v69, v67
	v_mov_b32_e32 v157, v69
	v_mov_b32_e32 v156, v67
	v_max_f32_e32 v69, v72, v72
	v_mul_f32_e32 v67, v70, v71
	v_min_f32_e32 v69, 0x42a00000, v69
	v_max_f32_e32 v70, v73, v73
	v_exp_f32_e32 v69, v69
	v_min_f32_e32 v70, 0x42a00000, v70
	v_exp_f32_e32 v70, v70
	v_mov_b32_e32 v158, v71
	v_mov_b32_e32 v159, v67
	v_add_f32_e32 v67, 1.0, v69
	v_rcp_f32_e32 v67, v67
	v_add_f32_e32 v71, 1.0, v70
	v_rcp_f32_e32 v71, v71
	v_mul_f32_e32 v69, v69, v67
	v_mov_b32_e32 v72, v69
	v_mul_f32_e32 v69, v70, v71
	v_max_f32_e32 v70, v74, v74
	v_max_f32_e32 v74, v75, v75
	v_min_f32_e32 v70, 0x42a00000, v70
	v_min_f32_e32 v74, 0x42a00000, v74
	v_exp_f32_e32 v70, v70
	v_exp_f32_e32 v74, v74
	v_mov_b32_e32 v73, v69
	v_add_f32_e32 v69, 1.0, v70
	v_add_f32_e32 v75, 1.0, v74
	v_rcp_f32_e32 v69, v69
	v_rcp_f32_e32 v75, v75
	v_max_f32_e32 v77, v77, v77
	v_mul_f32_e32 v70, v70, v69
	v_mov_b32_e32 v160, v69
	v_mul_f32_e32 v69, v74, v75
	v_max_f32_e32 v74, v76, v76
	v_min_f32_e32 v74, 0x42a00000, v74
	v_exp_f32_e32 v74, v74
	v_min_f32_e32 v77, 0x42a00000, v77
	v_exp_f32_e32 v77, v77
	v_mov_b32_e32 v76, v69
	v_add_f32_e32 v69, 1.0, v74
	v_rcp_f32_e32 v69, v69
	v_max_f32_e32 v78, v78, v78
	v_add_f32_e32 v137, 1.0, v77
	v_min_f32_e32 v78, 0x42a00000, v78
	v_rcp_f32_e32 v137, v137
	v_exp_f32_e32 v78, v78
	v_mul_f32_e32 v74, v74, v69
	v_max_f32_e32 v79, v79, v79
	v_min_f32_e32 v79, 0x42a00000, v79
	v_exp_f32_e32 v79, v79
	v_mul_f32_e32 v77, v77, v137
	v_mov_b32_e32 v161, v137
	v_add_f32_e32 v137, 1.0, v78
	v_rcp_f32_e32 v137, v137
	v_add_f32_e32 v162, 1.0, v79
	v_rcp_f32_e32 v162, v162
	v_mul_f32_e32 v78, v78, v137
	v_mov_b32_e32 v163, v137
	v_mul_f32_e32 v65, v65, v154
	v_mul_f32_e32 v137, v156, v158
	v_mul_f32_e32 v137, v65, v137
	v_mul_f32_e32 v79, v79, v162
	v_mov_b32_e32 v148, v162
	v_mov_b32_e32 v65, v137
	v_mov_b32_e32 v162, v137
	s_nop 1
	v_permlane32_swap_b32_e32 v65, v162
	v_cndmask_b32_e64 v65, v65, v162, s[0:1]
	v_mul_f32_e32 v67, v67, v71
	v_mul_f32_e32 v162, v160, v75
	v_mul_f32_e32 v67, v67, v162
	v_mov_b32_e32 v162, v67
	v_mov_b32_e32 v164, v67
	s_nop 1
	v_permlane32_swap_b32_e32 v162, v164
	v_cndmask_b32_e64 v162, v162, v164, s[0:1]
	v_mul_f32_e32 v69, v69, v161
	v_mul_f32_e32 v164, v163, v148
	v_mul_f32_e32 v69, v69, v164
	v_mov_b32_e32 v164, v69
	v_mov_b32_e32 v165, v69
	s_nop 1
	v_permlane32_swap_b32_e32 v164, v165
	v_cndmask_b32_e64 v164, v164, v165, s[0:1]
	v_cndmask_b32_e64 v165, 1.0, v164, s[0:1]
	v_mul_f32_e32 v69, v69, v164
	v_mul_f32_e32 v165, v146, v165
	v_mul_f32_e32 v69, v146, v69
	v_cndmask_b32_e64 v146, 1.0, v162, s[0:1]
	v_mul_f32_e32 v146, v146, v69
	v_mul_f32_e32 v148, v148, v165
	v_mul_f32_e32 v75, v75, v146
	v_mul_f32_e32 v163, v163, v148
	v_mul_f32_e32 v78, v78, v148
	v_mul_f32_e32 v148, v160, v75
	v_mul_f32_e32 v71, v71, v148
	v_mul_f32_e32 v67, v67, v162
	v_mul_f32_e32 v75, v70, v75
	v_mul_f32_e32 v148, v73, v148
	v_mul_f32_e32 v160, v72, v71
	v_pk_mul_f32 v[70:71], v[66:67], v[68:69]
	v_pk_mul_f32 v[72:73], v[136:137], v[64:65]
	v_mul_f32_e32 v76, v76, v146
	v_pk_mul_f32 v[72:73], v[72:73], v[70:71]
	v_cndmask_b32_e64 v146, 1.0, v65, s[0:1]
	v_mov_b32_e32 v65, v72
	v_mov_b32_e32 v67, v72
	s_nop 1
	v_permlane32_swap_b32_e32 v65, v67
	v_cndmask_b32_e64 v65, v65, v67, s[0:1]
	v_cndmask_b32_e64 v136, 1.0, v65, s[0:1]
	v_mul_f32_e32 v67, v146, v71
	v_mul_f32_e32 v136, v136, v73
	v_mul_f32_e32 v69, v158, v67
	v_mul_f32_e32 v68, v68, v136
	v_mul_f32_e32 v70, v156, v69
	v_mul_f32_e32 v66, v66, v68
	v_mul_f32_e32 v161, v161, v163
	v_mul_f32_e32 v71, v154, v70
	v_mul_f32_e32 v64, v64, v66
	v_mul_f32_e32 v65, v72, v65
	v_mul_f32_e32 v79, v79, v165
	v_mul_f32_e32 v77, v77, v163
	v_mul_f32_e32 v74, v74, v161
	v_mul_f32_e32 v67, v159, v67
	v_mul_f32_e32 v69, v157, v69
	v_mul_f32_e32 v70, v155, v70
	v_mul_f32_e32 v71, v153, v71
	v_mul_f32_e32 v136, v151, v136
	v_mul_f32_e32 v68, v152, v68
	v_mul_f32_e32 v66, v150, v66
	v_mul_f32_e32 v64, v149, v64
	v_mul_f32_e32 v146, v65, v73
	v_cvt_pk_bf16_f32 v64, v64, v66
	v_cvt_pk_bf16_f32 v65, v68, v136
	v_cvt_pk_bf16_f32 v66, v71, v70
	v_cvt_pk_bf16_f32 v67, v69, v67
	v_cvt_pk_bf16_f32 v68, v160, v148
	v_cvt_pk_bf16_f32 v69, v75, v76
	v_cvt_pk_bf16_f32 v70, v74, v77
	v_cvt_pk_bf16_f32 v71, v78, v79
	v_cmp_gt_f32_e32 vcc, s55, v146
	s_waitcnt lgkmcnt(0)
	v_mfma_f32_32x32x16_bf16 v[48:63], v[116:119], v[64:67], v[48:63]
	ds_read_b64_tr_b16 v[72:73], v147 offset:17536
	ds_read_b64_tr_b16 v[74:75], v147 offset:20096
	v_mfma_f32_32x32x16_bf16 v[32:47], v[112:115], v[64:67], v[32:47]
	ds_read_b64_tr_b16 v[76:77], v147 offset:17600
	ds_read_b64_tr_b16 v[78:79], v147 offset:20160
	s_waitcnt lgkmcnt(0)
	v_mfma_f32_32x32x16_bf16 v[16:31], v[72:75], v[64:67], v[16:31]
	ds_read_b64_tr_b16 v[112:113], v147 offset:22528
	ds_read_b64_tr_b16 v[114:115], v147 offset:25088
	v_mfma_f32_32x32x16_bf16 v[0:15], v[76:79], v[64:67], v[0:15]
	ds_read_b64_tr_b16 v[72:73], v147 offset:22592
	ds_read_b64_tr_b16 v[74:75], v147 offset:25152
	s_waitcnt lgkmcnt(0)
	v_mfma_f32_32x32x16_bf16 v[48:63], v[112:115], v[68:71], v[48:63]
	ds_read_b64_tr_b16 v[64:65], v147 offset:22656
	ds_read_b64_tr_b16 v[66:67], v147 offset:25216
	v_mfma_f32_32x32x16_bf16 v[32:47], v[72:75], v[68:71], v[32:47]
	ds_read_b64_tr_b16 v[76:77], v147 offset:22720
	ds_read_b64_tr_b16 v[78:79], v147 offset:25280
	s_waitcnt lgkmcnt(0)
	v_mfma_f32_32x32x16_bf16 v[16:31], v[64:67], v[68:71], v[16:31]
	v_mfma_f32_32x32x16_bf16 v[0:15], v[76:79], v[68:71], v[0:15]
	s_cmp_eq_u64 vcc, exec
	s_cselect_b64 s[42:43], -1, 0
	s_branch .Lsb_join_b
